# ADIFF fast path: QK block reordered (4 S0 k-steps then 4 S1 k-steps) so S0 softmax VALU starts 4 MFMAs earlier; rest = stack G
# speedup vs baseline: 1.0252x; 1.0222x over previous
; #define LAS __attribute__((address_space(3)))
; __device__ __forceinline__ void diff_attn_phase(const Params& p, LAS unsigned char* lds) {
;     ...
;                 for (int ks = 0; ks < 4; ++ks) kf[ks] = *(const LAS bf16x8*)(Ku + kbase + (kxl ^ (32 * ks)));
;                 bf16x8 P[2][2];
; #pragma unroll
;                 for (int r = 0; r < 2; ++r) {
;                     f32x16 S;
; #pragma unroll
;                     for (int i = 0; i < 16; ++i) S[i] = 0.f;
; #pragma unroll
;                     for (int ks = 0; ks < 4; ++ks) S = __builtin_amdgcn_mfma_f32_32x32x16_bf16(kf[ks], qf[r][ks], S, 0, 0, 0);
;                     S = __builtin_amdgcn_mfma_f32_32x32x16_bf16(kone, qm[r], S, 0, 0, 0);
; #pragma unroll
;                     for (int i = 0; i < 16; ++i) S[i] = __builtin_amdgcn_exp2f(S[i]);
;                     l[r] += sum16(S);
;                     P[r][0] = pack8(S, 0); P[r][1] = pack8(S, 8);
;                 }
; #pragma unroll
;                 for (int t = 0; t < 4; ++t) {
;                     const LAS unsigned char* a0 = Vu + (vb0l ^ (64 * t)); const LAS unsigned char* a1 = Vu + (vb1l ^ (64 * t));
;                     const bf16x8 v0 = tr_pair(a0, a1), v1 = tr_pair(a0 + 4096, a1 + 4096);
;                     O[0][t] = __builtin_amdgcn_mfma_f32_32x32x16_bf16(v0, P[0][0], O[0][t], 0, 0, 0);
;                     O[1][t] = __builtin_amdgcn_mfma_f32_32x32x16_bf16(v0, P[1][0], O[1][t], 0, 0, 0);
;                     O[0][t] = __builtin_amdgcn_mfma_f32_32x32x16_bf16(v1, P[0][1], O[0][t], 0, 0, 0);
;                     O[1][t] = __builtin_amdgcn_mfma_f32_32x32x16_bf16(v1, P[1][1], O[1][t], 0, 0, 0);
.Lfb_loopF:
	s_waitcnt lgkmcnt(3)
	v_mfma_f32_32x32x16_bf16 v[146:161], v[198:201], v[166:169], 0
	s_waitcnt lgkmcnt(2)
	v_mfma_f32_32x32x16_bf16 v[146:161], v[202:205], v[170:173], v[146:161]
	s_waitcnt lgkmcnt(1)
	v_mfma_f32_32x32x16_bf16 v[146:161], v[208:211], v[174:177], v[146:161]
	s_waitcnt lgkmcnt(0)
	v_mfma_f32_32x32x16_bf16 v[146:161], v[230:233], v[178:181], v[146:161]
	v_mfma_f32_32x32x16_bf16 v[130:145], v[198:201], v[182:185], 0
	ds_read_b64_tr_b16 v[198:199], v234 offset:16384
	ds_read_b64_tr_b16 v[200:201], v235 offset:16384
	v_mfma_f32_32x32x16_bf16 v[130:145], v[202:205], v[186:189], v[130:145]
	ds_read_b64_tr_b16 v[202:203], v237 offset:16384
	ds_read_b64_tr_b16 v[204:205], v236 offset:16384
	v_mfma_f32_32x32x16_bf16 v[130:145], v[208:211], v[190:193], v[130:145]
	ds_read_b64_tr_b16 v[208:209], v238 offset:16384
	ds_read_b64_tr_b16 v[210:211], v239 offset:16384
	v_mfma_f32_32x32x16_bf16 v[130:145], v[230:233], v[194:197], v[130:145]
	ds_read_b64_tr_b16 v[230:231], v250 offset:16384
	ds_read_b64_tr_b16 v[232:233], v251 offset:16384
	v_exp_f32_e32 v146, v146
	v_exp_f32_e32 v147, v147
	v_exp_f32_e32 v148, v148
	v_exp_f32_e32 v149, v149
	v_add_f32_e32 v213, v213, v146
	s_waitcnt lgkmcnt(6)
	v_mfma_f32_32x32x16_bf16 v[114:129], v[198:201], v[214:217], v[114:129]
	v_add_f32_e32 v213, v213, v147
	v_add_f32_e32 v213, v213, v148
	v_add_f32_e32 v213, v213, v149
	v_exp_f32_e32 v150, v150
	v_exp_f32_e32 v151, v151
	v_mfma_f32_32x32x16_bf16 v[50:65], v[198:201], v[218:221], v[50:65]
	ds_read_b64_tr_b16 v[198:199], v234 offset:20480
	ds_read_b64_tr_b16 v[200:201], v235 offset:20480
	v_exp_f32_e32 v152, v152
	v_exp_f32_e32 v153, v153
	v_add_f32_e32 v213, v213, v150
	v_add_f32_e32 v213, v213, v151
	v_add_f32_e32 v213, v213, v152
	s_waitcnt lgkmcnt(6)
	v_mfma_f32_32x32x16_bf16 v[98:113], v[202:205], v[214:217], v[98:113]
	v_add_f32_e32 v213, v213, v153
	v_exp_f32_e32 v154, v154
	v_exp_f32_e32 v155, v155
	v_exp_f32_e32 v156, v156
	v_exp_f32_e32 v157, v157
	v_mfma_f32_32x32x16_bf16 v[34:49], v[202:205], v[218:221], v[34:49]
	ds_read_b64_tr_b16 v[202:203], v237 offset:20480
	ds_read_b64_tr_b16 v[204:205], v236 offset:20480
	v_add_f32_e32 v213, v213, v154
	v_add_f32_e32 v213, v213, v155
	v_add_f32_e32 v213, v213, v156
	v_add_f32_e32 v213, v213, v157
	s_waitcnt lgkmcnt(6)
	v_mfma_f32_32x32x16_bf16 v[82:97], v[208:211], v[214:217], v[82:97]
	v_exp_f32_e32 v158, v158
	v_exp_f32_e32 v159, v159
	v_exp_f32_e32 v160, v160
	v_exp_f32_e32 v161, v161
	v_mfma_f32_32x32x16_bf16 v[18:33], v[208:211], v[218:221], v[18:33]
	ds_read_b64_tr_b16 v[208:209], v238 offset:20480
	ds_read_b64_tr_b16 v[210:211], v239 offset:20480
	v_add_f32_e32 v213, v213, v158
	v_add_f32_e32 v213, v213, v159
	v_add_f32_e32 v213, v213, v160
	v_add_f32_e32 v213, v213, v161
	s_waitcnt lgkmcnt(6)
	v_mfma_f32_32x32x16_bf16 v[66:81], v[230:233], v[214:217], v[66:81]
	v_exp_f32_e32 v130, v130
	v_exp_f32_e32 v131, v131
	v_exp_f32_e32 v132, v132
	v_exp_f32_e32 v133, v133
	v_mfma_f32_32x32x16_bf16 v[2:17], v[230:233], v[218:221], v[2:17]
	ds_read_b64_tr_b16 v[230:231], v250 offset:20480
	ds_read_b64_tr_b16 v[232:233], v251 offset:20480
	v_add_f32_e32 v212, v212, v130
	v_add_f32_e32 v212, v212, v131
	v_add_f32_e32 v212, v212, v132
	v_add_f32_e32 v212, v212, v133
	s_cmpk_eq_u32 s29, 0x7f
	s_cbranch_scc1 .Lfb_last0F
	s_cmpk_eq_u32 s29, 0x7e
	s_cbranch_scc1 .Lfb_w0F
	s_waitcnt vmcnt(4)
	s_branch .Lfb_w1F

; #define LAS __attribute__((address_space(3)))
; __device__ __forceinline__ void diff_attn_phase(const Params& p, LAS unsigned char* lds) {
;     ...
;                 bf16x8 P[2][2];
; #pragma unroll
;                 for (int r = 0; r < 2; ++r) {
;                     f32x16 S;
; #pragma unroll
;                     for (int i = 0; i < 16; ++i) S[i] = 0.f;
; #pragma unroll
;                     for (int ks = 0; ks < 4; ++ks) S = __builtin_amdgcn_mfma_f32_32x32x16_bf16(kf[ks], qf[r][ks], S, 0, 0, 0);
;                     S = __builtin_amdgcn_mfma_f32_32x32x16_bf16(kone, qm[r], S, 0, 0, 0);
; #pragma unroll
;                     for (int i = 0; i < 16; ++i) S[i] = __builtin_amdgcn_exp2f(S[i]);
;                     l[r] += sum16(S);
;                     P[r][0] = pack8(S, 0); P[r][1] = pack8(S, 8);
;                 }
; #pragma unroll
;                 for (int t = 0; t < 4; ++t) {
;                     const LAS unsigned char* a0 = Vu + (vb0l ^ (64 * t)); const LAS unsigned char* a1 = Vu + (vb1l ^ (64 * t));
;                     const bf16x8 v0 = tr_pair(a0, a1), v1 = tr_pair(a0 + 4096, a1 + 4096);
;                     O[0][t] = __builtin_amdgcn_mfma_f32_32x32x16_bf16(v0, P[0][0], O[0][t], 0, 0, 0);
;                     O[1][t] = __builtin_amdgcn_mfma_f32_32x32x16_bf16(v0, P[1][0], O[1][t], 0, 0, 0);
;                     O[0][t] = __builtin_amdgcn_mfma_f32_32x32x16_bf16(v1, P[0][1], O[0][t], 0, 0, 0);
;                     O[1][t] = __builtin_amdgcn_mfma_f32_32x32x16_bf16(v1, P[1][1], O[1][t], 0, 0, 0);
;                 }
.Lfb_nodmaF:
	s_add_i32 s2, s29, 1
	s_and_b32 s2, s2, 3
	s_mov_b32 s37, 0x8000
	s_cmp_eq_u32 s2, 0
	s_cselect_b32 s37, 0xfffe8000, s37
	v_add_u32_e32 v1, s37, v1
	s_waitcnt lgkmcnt(6)
	v_mfma_f32_32x32x16_bf16 v[114:129], v[198:201], v[222:225], v[114:129]
	v_exp_f32_e32 v134, v134
	v_exp_f32_e32 v135, v135
	v_exp_f32_e32 v136, v136
	v_exp_f32_e32 v137, v137
	v_mfma_f32_32x32x16_bf16 v[50:65], v[198:201], v[226:229], v[50:65]
	v_add_u32_e32 v198, v246, v1
	ds_read_b128 v[198:201], v198
	v_add_f32_e32 v212, v212, v134
	v_add_f32_e32 v212, v212, v135
	v_add_f32_e32 v212, v212, v136
	v_add_f32_e32 v212, v212, v137
	s_waitcnt lgkmcnt(5)
	v_mfma_f32_32x32x16_bf16 v[98:113], v[202:205], v[222:225], v[98:113]
	v_exp_f32_e32 v138, v138
	v_exp_f32_e32 v139, v139
	v_exp_f32_e32 v140, v140
	v_exp_f32_e32 v141, v141
	v_mfma_f32_32x32x16_bf16 v[34:49], v[202:205], v[226:229], v[34:49]
	v_xad_u32 v202, v246, 32, v1
	ds_read_b128 v[202:205], v202
	v_add_f32_e32 v212, v212, v138
	v_add_f32_e32 v212, v212, v139
	v_add_f32_e32 v212, v212, v140
	v_add_f32_e32 v212, v212, v141
	s_waitcnt lgkmcnt(4)
	v_mfma_f32_32x32x16_bf16 v[82:97], v[208:211], v[222:225], v[82:97]
	v_exp_f32_e32 v142, v142
	v_exp_f32_e32 v143, v143
	v_exp_f32_e32 v144, v144
	v_exp_f32_e32 v145, v145
	v_mfma_f32_32x32x16_bf16 v[18:33], v[208:211], v[226:229], v[18:33]
	v_xad_u32 v208, v246, 64, v1
	ds_read_b128 v[208:211], v208
	v_add_f32_e32 v212, v212, v142
	v_add_f32_e32 v212, v212, v143
	v_add_f32_e32 v212, v212, v144
	v_add_f32_e32 v212, v212, v145
	s_waitcnt lgkmcnt(3)
	v_mfma_f32_32x32x16_bf16 v[66:81], v[230:233], v[222:225], v[66:81]
	v_cvt_pk_bf16_f32 v214, v146, v147
	v_cvt_pk_bf16_f32 v218, v130, v131
	v_cvt_pk_bf16_f32 v215, v148, v149
	v_cvt_pk_bf16_f32 v219, v132, v133
	v_cvt_pk_bf16_f32 v216, v150, v151
	v_cvt_pk_bf16_f32 v220, v134, v135
	v_cvt_pk_bf16_f32 v217, v152, v153
	v_cvt_pk_bf16_f32 v221, v136, v137
	v_mfma_f32_32x32x16_bf16 v[2:17], v[230:233], v[226:229], v[2:17]
	v_xad_u32 v230, v246, s47, v1
	ds_read_b128 v[230:233], v230
	v_cvt_pk_bf16_f32 v222, v154, v155
	v_cvt_pk_bf16_f32 v226, v138, v139
	v_cvt_pk_bf16_f32 v223, v156, v157
	v_cvt_pk_bf16_f32 v227, v140, v141
	v_cvt_pk_bf16_f32 v224, v158, v159
	v_cvt_pk_bf16_f32 v228, v142, v143
	v_cvt_pk_bf16_f32 v225, v160, v161
	v_cvt_pk_bf16_f32 v229, v144, v145
	s_waitcnt lgkmcnt(3)
	v_mfma_f32_32x32x16_bf16 v[146:161], v[198:201], v[166:169], 0
	s_waitcnt lgkmcnt(2)
	v_mfma_f32_32x32x16_bf16 v[146:161], v[202:205], v[170:173], v[146:161]
	s_waitcnt lgkmcnt(1)
	v_mfma_f32_32x32x16_bf16 v[146:161], v[208:211], v[174:177], v[146:161]
	s_waitcnt lgkmcnt(0)
	v_mfma_f32_32x32x16_bf16 v[146:161], v[230:233], v[178:181], v[146:161]
	v_mfma_f32_32x32x16_bf16 v[130:145], v[198:201], v[182:185], 0
	ds_read_b64_tr_b16 v[198:199], v234 offset:24576
	ds_read_b64_tr_b16 v[200:201], v235 offset:24576
	v_mfma_f32_32x32x16_bf16 v[130:145], v[202:205], v[186:189], v[130:145]
	ds_read_b64_tr_b16 v[202:203], v237 offset:24576
	ds_read_b64_tr_b16 v[204:205], v236 offset:24576
	v_mfma_f32_32x32x16_bf16 v[130:145], v[208:211], v[190:193], v[130:145]
	ds_read_b64_tr_b16 v[208:209], v238 offset:24576
	ds_read_b64_tr_b16 v[210:211], v239 offset:24576
	v_mfma_f32_32x32x16_bf16 v[130:145], v[230:233], v[194:197], v[130:145]
	ds_read_b64_tr_b16 v[230:231], v250 offset:24576
	ds_read_b64_tr_b16 v[232:233], v251 offset:24576
	v_exp_f32_e32 v146, v146
	v_exp_f32_e32 v147, v147
	v_exp_f32_e32 v148, v148
	v_exp_f32_e32 v149, v149
	v_add_f32_e32 v213, v213, v146
	s_waitcnt lgkmcnt(6)
	v_mfma_f32_32x32x16_bf16 v[114:129], v[198:201], v[214:217], v[114:129]
	v_add_f32_e32 v213, v213, v147
	v_add_f32_e32 v213, v213, v148
	v_add_f32_e32 v213, v213, v149
	v_exp_f32_e32 v150, v150
	v_exp_f32_e32 v151, v151
	v_mfma_f32_32x32x16_bf16 v[50:65], v[198:201], v[218:221], v[50:65]
	ds_read_b64_tr_b16 v[198:199], v234 offset:28672
	ds_read_b64_tr_b16 v[200:201], v235 offset:28672
	v_exp_f32_e32 v152, v152
	v_exp_f32_e32 v153, v153
	v_add_f32_e32 v213, v213, v150
	v_add_f32_e32 v213, v213, v151
	v_add_f32_e32 v213, v213, v152
	s_waitcnt lgkmcnt(6)
	v_mfma_f32_32x32x16_bf16 v[98:113], v[202:205], v[214:217], v[98:113]
	v_add_f32_e32 v213, v213, v153
	v_exp_f32_e32 v154, v154
	v_exp_f32_e32 v155, v155
	v_exp_f32_e32 v156, v156
	v_exp_f32_e32 v157, v157
	v_mfma_f32_32x32x16_bf16 v[34:49], v[202:205], v[218:221], v[34:49]
	ds_read_b64_tr_b16 v[202:203], v237 offset:28672
	ds_read_b64_tr_b16 v[204:205], v236 offset:28672
	v_add_f32_e32 v213, v213, v154
	v_add_f32_e32 v213, v213, v155
	v_add_f32_e32 v213, v213, v156
	v_add_f32_e32 v213, v213, v157
	s_waitcnt lgkmcnt(6)
	v_mfma_f32_32x32x16_bf16 v[82:97], v[208:211], v[214:217], v[82:97]
	v_exp_f32_e32 v158, v158
	v_exp_f32_e32 v159, v159
	v_exp_f32_e32 v160, v160
	v_exp_f32_e32 v161, v161
	v_mfma_f32_32x32x16_bf16 v[18:33], v[208:211], v[218:221], v[18:33]
	ds_read_b64_tr_b16 v[208:209], v238 offset:28672
	ds_read_b64_tr_b16 v[210:211], v239 offset:28672
	v_add_f32_e32 v213, v213, v158
	v_add_f32_e32 v213, v213, v159
	v_add_f32_e32 v213, v213, v160
	v_add_f32_e32 v213, v213, v161
	s_waitcnt lgkmcnt(6)
	v_mfma_f32_32x32x16_bf16 v[66:81], v[230:233], v[214:217], v[66:81]
	v_exp_f32_e32 v130, v130
	v_exp_f32_e32 v131, v131
	v_exp_f32_e32 v132, v132
	v_exp_f32_e32 v133, v133
	v_mfma_f32_32x32x16_bf16 v[2:17], v[230:233], v[218:221], v[2:17]
	ds_read_b64_tr_b16 v[230:231], v250 offset:28672
	ds_read_b64_tr_b16 v[232:233], v251 offset:28672
	v_add_f32_e32 v212, v212, v130
	v_add_f32_e32 v212, v212, v131
	v_add_f32_e32 v212, v212, v132
	v_add_f32_e32 v212, v212, v133
	v_add_u32_e32 v234, s37, v234
	v_add_u32_e32 v235, s37, v235
	v_add_u32_e32 v237, s37, v237
	v_add_u32_e32 v236, s37, v236
	v_add_u32_e32 v238, s37, v238
	v_add_u32_e32 v239, s37, v239
	v_add_u32_e32 v250, s37, v250
	v_add_u32_e32 v251, s37, v251
	s_waitcnt lgkmcnt(6)
; #define LAS __attribute__((address_space(3)))
; __device__ __forceinline__ void diff_attn_phase(const Params& p, LAS unsigned char* lds) {
;     ...
;                 bf16x8 P[2][2];
; #pragma unroll
;                 for (int r = 0; r < 2; ++r) {
;                     f32x16 S;
; #pragma unroll
;                     for (int i = 0; i < 16; ++i) S[i] = 0.f;
; #pragma unroll
;                     for (int ks = 0; ks < 4; ++ks) S = __builtin_amdgcn_mfma_f32_32x32x16_bf16(kf[ks], qf[r][ks], S, 0, 0, 0);
;                     S = __builtin_amdgcn_mfma_f32_32x32x16_bf16(kone, qm[r], S, 0, 0, 0);
; #pragma unroll
;                     for (int i = 0; i < 16; ++i) S[i] = __builtin_amdgcn_exp2f(S[i]);
;                     l[r] += sum16(S);
;                     P[r][0] = pack8(S, 0); P[r][1] = pack8(S, 8);
;                 }
; #pragma unroll
;                 for (int t = 0; t < 4; ++t) {
;                     const LAS unsigned char* a0 = Vu + (vb0l ^ (64 * t)); const LAS unsigned char* a1 = Vu + (vb1l ^ (64 * t));
;                     const bf16x8 v0 = tr_pair(a0, a1), v1 = tr_pair(a0 + 4096, a1 + 4096);
;                     O[0][t] = __builtin_amdgcn_mfma_f32_32x32x16_bf16(v0, P[0][0], O[0][t], 0, 0, 0);
;                     O[1][t] = __builtin_amdgcn_mfma_f32_32x32x16_bf16(v0, P[1][0], O[1][t], 0, 0, 0);
;                     O[0][t] = __builtin_amdgcn_mfma_f32_32x32x16_bf16(v1, P[0][1], O[0][t], 0, 0, 0);
;                     O[1][t] = __builtin_amdgcn_mfma_f32_32x32x16_bf16(v1, P[1][1], O[1][t], 0, 0, 0);
;                 }
	v_mfma_f32_32x32x16_bf16 v[114:129], v[198:201], v[222:225], v[114:129]
	v_exp_f32_e32 v134, v134
	v_exp_f32_e32 v135, v135
	v_exp_f32_e32 v136, v136
	v_exp_f32_e32 v137, v137
	v_mfma_f32_32x32x16_bf16 v[50:65], v[198:201], v[226:229], v[50:65]
	v_add_u32_e32 v198, v246, v1
	ds_read_b128 v[198:201], v198 offset:8192
	v_add_f32_e32 v212, v212, v134
	v_add_f32_e32 v212, v212, v135
	v_add_f32_e32 v212, v212, v136
	v_add_f32_e32 v212, v212, v137
	s_waitcnt lgkmcnt(5)
	v_mfma_f32_32x32x16_bf16 v[98:113], v[202:205], v[222:225], v[98:113]
	v_exp_f32_e32 v138, v138
	v_exp_f32_e32 v139, v139
	v_exp_f32_e32 v140, v140
	v_exp_f32_e32 v141, v141
	v_mfma_f32_32x32x16_bf16 v[34:49], v[202:205], v[226:229], v[34:49]
	v_xad_u32 v202, v246, 32, v1
	ds_read_b128 v[202:205], v202 offset:8192
	v_add_f32_e32 v212, v212, v138
	v_add_f32_e32 v212, v212, v139
	v_add_f32_e32 v212, v212, v140
	v_add_f32_e32 v212, v212, v141
	s_waitcnt lgkmcnt(4)
	v_mfma_f32_32x32x16_bf16 v[82:97], v[208:211], v[222:225], v[82:97]
	v_exp_f32_e32 v142, v142
	v_exp_f32_e32 v143, v143
	v_exp_f32_e32 v144, v144
	v_exp_f32_e32 v145, v145
	v_mfma_f32_32x32x16_bf16 v[18:33], v[208:211], v[226:229], v[18:33]
	v_xad_u32 v208, v246, 64, v1
	ds_read_b128 v[208:211], v208 offset:8192
	v_add_f32_e32 v212, v212, v142
	v_add_f32_e32 v212, v212, v143
	v_add_f32_e32 v212, v212, v144
	v_add_f32_e32 v212, v212, v145
	s_waitcnt lgkmcnt(3)
	v_mfma_f32_32x32x16_bf16 v[66:81], v[230:233], v[222:225], v[66:81]
	v_cvt_pk_bf16_f32 v214, v146, v147
	v_cvt_pk_bf16_f32 v218, v130, v131
	v_cvt_pk_bf16_f32 v215, v148, v149
	v_cvt_pk_bf16_f32 v219, v132, v133
	v_cvt_pk_bf16_f32 v216, v150, v151
	v_cvt_pk_bf16_f32 v220, v134, v135
	v_cvt_pk_bf16_f32 v217, v152, v153
	v_cvt_pk_bf16_f32 v221, v136, v137
	v_mfma_f32_32x32x16_bf16 v[2:17], v[230:233], v[226:229], v[2:17]
	v_xad_u32 v230, v246, s47, v1
	ds_read_b128 v[230:233], v230 offset:8192
	v_cvt_pk_bf16_f32 v222, v154, v155
	v_cvt_pk_bf16_f32 v226, v138, v139
	v_cvt_pk_bf16_f32 v223, v156, v157
	v_cvt_pk_bf16_f32 v227, v140, v141
	v_cvt_pk_bf16_f32 v224, v158, v159
	v_cvt_pk_bf16_f32 v228, v142, v143
	v_cvt_pk_bf16_f32 v225, v160, v161
	v_cvt_pk_bf16_f32 v229, v144, v145
	s_add_i32 s29, s29, 1
	s_branch .Lfb_loopF
.Lfb_last0F:
	s_waitcnt lgkmcnt(6)
	v_mfma_f32_32x32x16_bf16 v[114:129], v[198:201], v[222:225], v[114:129]
	v_exp_f32_e32 v134, v134
	v_exp_f32_e32 v135, v135
	v_exp_f32_e32 v136, v136
	v_exp_f32_e32 v137, v137
	v_mfma_f32_32x32x16_bf16 v[50:65], v[198:201], v[226:229], v[50:65]
	ds_read_b64_tr_b16 v[198:199], v234 offset:24576
	ds_read_b64_tr_b16 v[200:201], v235 offset:24576
	v_add_f32_e32 v212, v212, v134
	v_add_f32_e32 v212, v212, v135
	v_add_f32_e32 v212, v212, v136
	v_add_f32_e32 v212, v212, v137
	s_waitcnt lgkmcnt(6)
	v_mfma_f32_32x32x16_bf16 v[98:113], v[202:205], v[222:225], v[98:113]
	v_exp_f32_e32 v138, v138
	v_exp_f32_e32 v139, v139
	v_exp_f32_e32 v140, v140
	v_exp_f32_e32 v141, v141
	v_mfma_f32_32x32x16_bf16 v[34:49], v[202:205], v[226:229], v[34:49]
	ds_read_b64_tr_b16 v[202:203], v237 offset:24576
	ds_read_b64_tr_b16 v[204:205], v236 offset:24576
	v_add_f32_e32 v212, v212, v138
	v_add_f32_e32 v212, v212, v139
	v_add_f32_e32 v212, v212, v140
	v_add_f32_e32 v212, v212, v141
	s_waitcnt lgkmcnt(6)
	v_mfma_f32_32x32x16_bf16 v[82:97], v[208:211], v[222:225], v[82:97]
	v_exp_f32_e32 v142, v142
	v_exp_f32_e32 v143, v143
	v_exp_f32_e32 v144, v144
	v_exp_f32_e32 v145, v145
	v_mfma_f32_32x32x16_bf16 v[18:33], v[208:211], v[226:229], v[18:33]
	ds_read_b64_tr_b16 v[208:209], v238 offset:24576
	ds_read_b64_tr_b16 v[210:211], v239 offset:24576
	v_add_f32_e32 v212, v212, v142
	v_add_f32_e32 v212, v212, v143
	v_add_f32_e32 v212, v212, v144
	v_add_f32_e32 v212, v212, v145
	s_waitcnt lgkmcnt(6)
	v_mfma_f32_32x32x16_bf16 v[66:81], v[230:233], v[222:225], v[66:81]
	v_cvt_pk_bf16_f32 v214, v146, v147
	v_cvt_pk_bf16_f32 v218, v130, v131
	v_cvt_pk_bf16_f32 v215, v148, v149
	v_cvt_pk_bf16_f32 v219, v132, v133
	v_cvt_pk_bf16_f32 v216, v150, v151
	v_cvt_pk_bf16_f32 v220, v134, v135
	v_cvt_pk_bf16_f32 v217, v152, v153
	v_cvt_pk_bf16_f32 v221, v136, v137
	v_mfma_f32_32x32x16_bf16 v[2:17], v[230:233], v[226:229], v[2:17]
	ds_read_b64_tr_b16 v[230:231], v250 offset:24576
	ds_read_b64_tr_b16 v[232:233], v251 offset:24576
	v_cvt_pk_bf16_f32 v222, v154, v155
	v_cvt_pk_bf16_f32 v226, v138, v139
	v_cvt_pk_bf16_f32 v223, v156, v157
	v_cvt_pk_bf16_f32 v227, v140, v141
	v_cvt_pk_bf16_f32 v224, v158, v159
	v_cvt_pk_bf16_f32 v228, v142, v143
	v_cvt_pk_bf16_f32 v225, v160, v161
	v_cvt_pk_bf16_f32 v229, v144, v145
	s_waitcnt lgkmcnt(6)
	v_mfma_f32_32x32x16_bf16 v[114:129], v[198:201], v[214:217], v[114:129]
	v_mfma_f32_32x32x16_bf16 v[50:65], v[198:201], v[218:221], v[50:65]
	ds_read_b64_tr_b16 v[198:199], v234 offset:28672
	ds_read_b64_tr_b16 v[200:201], v235 offset:28672
	s_waitcnt lgkmcnt(6)
	v_mfma_f32_32x32x16_bf16 v[98:113], v[202:205], v[214:217], v[98:113]
	v_mfma_f32_32x32x16_bf16 v[34:49], v[202:205], v[218:221], v[34:49]
	ds_read_b64_tr_b16 v[202:203], v237 offset:28672
	ds_read_b64_tr_b16 v[204:205], v236 offset:28672
	s_waitcnt lgkmcnt(6)
	v_mfma_f32_32x32x16_bf16 v[82:97], v[208:211], v[214:217], v[82:97]
	v_mfma_f32_32x32x16_bf16 v[18:33], v[208:211], v[218:221], v[18:33]
	ds_read_b64_tr_b16 v[208:209], v238 offset:28672
	ds_read_b64_tr_b16 v[210:211], v239 offset:28672
	s_waitcnt lgkmcnt(6)
	v_mfma_f32_32x32x16_bf16 v[66:81], v[230:233], v[214:217], v[66:81]
	v_mfma_f32_32x32x16_bf16 v[2:17], v[230:233], v[218:221], v[2:17]
	ds_read_b64_tr_b16 v[230:231], v250 offset:28672
	ds_read_b64_tr_b16 v[232:233], v251 offset:28672
	s_waitcnt lgkmcnt(6)
	v_mfma_f32_32x32x16_bf16 v[114:129], v[198:201], v[222:225], v[114:129]
	v_mfma_f32_32x32x16_bf16 v[50:65], v[198:201], v[226:229], v[50:65]
	s_waitcnt lgkmcnt(4)
	v_mfma_f32_32x32x16_bf16 v[98:113], v[202:205], v[222:225], v[98:113]
	v_mfma_f32_32x32x16_bf16 v[34:49], v[202:205], v[226:229], v[34:49]
	s_waitcnt lgkmcnt(2)
	v_mfma_f32_32x32x16_bf16 v[82:97], v[208:211], v[222:225], v[82:97]
	v_mfma_f32_32x32x16_bf16 v[18:33], v[208:211], v[226:229], v[18:33]
	s_waitcnt lgkmcnt(0)
	v_mfma_f32_32x32x16_bf16 v[66:81], v[230:233], v[222:225], v[66:81]
	v_mfma_f32_32x32x16_bf16 v[2:17], v[230:233], v[226:229], v[2:17]
	s_branch .Lad_epi
